# v79 + E3 attention output rows (both task kinds) staged through LDS and stored as 16-byte row chunks
# baseline (speedup 1.0000x reference)
.LBB0_1050:
	v_fma_f32 v48, v48, s97, -v135
	v_exp_f32_e32 v48, v48
	v_fma_f32 v49, v49, s97, -v135
	v_exp_f32_e32 v49, v49
	v_fma_f32 v50, v50, s97, -v135
	v_exp_f32_e32 v50, v50
	v_fma_f32 v51, v51, s97, -v135
	v_exp_f32_e32 v51, v51
	v_fma_f32 v52, v52, s97, -v135
	v_add_f32_e32 v134, v134, v48
	v_exp_f32_e32 v52, v52
	v_fma_f32 v53, v53, s97, -v135
	v_add_f32_e32 v134, v49, v134
	v_exp_f32_e32 v53, v53
	v_fma_f32 v54, v54, s97, -v135
	v_add_f32_e32 v134, v50, v134
	v_exp_f32_e32 v54, v54
	v_fma_f32 v55, v55, s97, -v135
	v_add_f32_e32 v134, v51, v134
	v_exp_f32_e32 v55, v55
	v_fma_f32 v56, v56, s97, -v135
	v_add_f32_e32 v134, v52, v134
	v_exp_f32_e32 v56, v56
	v_fma_f32 v57, v57, s97, -v135
	v_add_f32_e32 v134, v53, v134
	v_exp_f32_e32 v57, v57
	v_fma_f32 v58, v58, s97, -v135
	v_add_f32_e32 v134, v54, v134
	v_exp_f32_e32 v58, v58
	v_fma_f32 v59, v59, s97, -v135
	v_add_f32_e32 v134, v55, v134
	v_exp_f32_e32 v59, v59
	v_fma_f32 v60, v60, s97, -v135
	v_add_f32_e32 v134, v56, v134
	v_exp_f32_e32 v60, v60
	v_fma_f32 v61, v61, s97, -v135
	v_add_f32_e32 v134, v57, v134
	v_exp_f32_e32 v61, v61
	v_fma_f32 v62, v62, s97, -v135
	v_add_f32_e32 v134, v58, v134
	v_exp_f32_e32 v62, v62
	v_fma_f32 v63, v63, s97, -v135
	v_add_f32_e32 v134, v59, v134
	v_exp_f32_e32 v63, v63
	v_fma_f32 v32, v32, s97, -v135
	v_add_f32_e32 v134, v60, v134
	v_exp_f32_e32 v136, v32
	v_add_f32_e32 v32, v61, v134
	v_add_f32_e32 v32, v62, v32
	v_add_f32_e32 v32, v63, v32
	v_add_f32_e32 v134, v136, v32
	v_fma_f32 v32, v33, s97, -v135
	v_exp_f32_e32 v137, v32
	v_fma_f32 v32, v34, s97, -v135
	v_exp_f32_e32 v144, v32
	v_fma_f32 v32, v35, s97, -v135
	v_exp_f32_e32 v145, v32
	v_fma_f32 v32, v36, s97, -v135
	v_exp_f32_e32 v36, v32
	v_cvt_pk_bf16_f32 v32, v48, v49
	v_cvt_pk_bf16_f32 v33, v50, v51
	v_cvt_pk_bf16_f32 v34, v52, v53
	v_cvt_pk_bf16_f32 v35, v54, v55
	v_fma_f32 v37, v37, s97, -v135
	v_fma_f32 v38, v38, s97, -v135
	s_waitcnt lgkmcnt(7)
	v_mfma_f32_32x32x16_bf16 v[16:31], v[112:115], v[32:35], v[16:31]
	v_exp_f32_e32 v37, v37
	v_exp_f32_e32 v38, v38
	v_add_f32_e32 v48, v137, v134
	v_add_f32_e32 v48, v144, v48
	v_add_f32_e32 v48, v145, v48
	v_add_f32_e32 v48, v36, v48
	v_add_f32_e32 v48, v37, v48
	s_waitcnt lgkmcnt(5)
	v_mfma_f32_32x32x16_bf16 v[0:15], v[116:119], v[32:35], v[0:15]
	v_fma_f32 v32, v39, s97, -v135
	v_exp_f32_e32 v39, v32
	v_cvt_pk_bf16_f32 v32, v56, v57
	v_cvt_pk_bf16_f32 v33, v58, v59
	v_cvt_pk_bf16_f32 v34, v60, v61
	v_cvt_pk_bf16_f32 v35, v62, v63
	v_add_f32_e32 v48, v38, v48
	v_fma_f32 v40, v40, s97, -v135
	v_mfma_f32_32x32x16_bf16 v[16:31], v[104:107], v[32:35], v[16:31]
	v_add_f32_e32 v48, v39, v48
	v_fma_f32 v41, v41, s97, -v135
	v_exp_f32_e32 v40, v40
	v_exp_f32_e32 v41, v41
	s_mov_b64 s[2:3], 0x10000
	s_add_i32 s5, s5, 1
	v_add_f32_e32 v48, v40, v48
	s_waitcnt lgkmcnt(4)
	v_mfma_f32_32x32x16_bf16 v[0:15], v[108:111], v[32:35], v[0:15]
	v_fma_f32 v32, v42, s97, -v135
	v_exp_f32_e32 v42, v32
	v_cvt_pk_bf16_f32 v32, v136, v137
	v_cvt_pk_bf16_f32 v33, v144, v145
	v_cvt_pk_bf16_f32 v34, v36, v37
	v_cvt_pk_bf16_f32 v35, v38, v39
	v_fma_f32 v36, v43, s97, -v135
	v_fma_f32 v37, v44, s97, -v135
	s_waitcnt lgkmcnt(3)
	v_mfma_f32_32x32x16_bf16 v[16:31], v[100:103], v[32:35], v[16:31]
	v_fma_f32 v38, v45, s97, -v135
	v_fma_f32 v39, v46, s97, -v135
	v_exp_f32_e32 v36, v36
	v_exp_f32_e32 v37, v37
	v_exp_f32_e32 v38, v38
	v_exp_f32_e32 v39, v39
	v_lshl_add_u64 v[124:125], v[124:125], 0, s[2:3]
	s_waitcnt lgkmcnt(2)
	v_mfma_f32_32x32x16_bf16 v[0:15], v[96:99], v[32:35], v[0:15]
	v_fma_f32 v32, v47, s97, -v135
	v_exp_f32_e32 v43, v32
	v_cvt_pk_bf16_f32 v32, v40, v41
	v_cvt_pk_bf16_f32 v33, v42, v36
	v_cvt_pk_bf16_f32 v34, v37, v38
	v_cvt_pk_bf16_f32 v35, v39, v43
	v_add_f32_e32 v40, v41, v48
	v_add_f32_e32 v40, v42, v40
	s_waitcnt lgkmcnt(1)
	v_mfma_f32_32x32x16_bf16 v[16:31], v[92:95], v[32:35], v[16:31]
	v_add_f32_e32 v36, v36, v40
	v_add_f32_e32 v36, v37, v36
	v_add_f32_e32 v36, v38, v36
	v_add_f32_e32 v36, v39, v36
	s_mov_b64 s[2:3], 0x80
	v_add_f32_e32 v134, v43, v36
	s_cmp_lg_u32 s5, 4
	s_waitcnt lgkmcnt(0)
	v_mfma_f32_32x32x16_bf16 v[0:15], v[88:91], v[32:35], v[0:15]
	v_lshl_add_u64 v[126:127], v[126:127], 0, s[2:3]
	s_cbranch_scc1 .LBB0_1041
	s_lshl_b64 s[0:1], s[72:73], 11
	v_readlane_b32 s2, v241, 51
	v_mov_b32_e32 v32, v134
	s_add_u32 s0, s2, s0
	v_readlane_b32 s2, v241, 52
	v_permlane32_swap_b32_e32 v134, v32
	s_addc_u32 s1, s2, s1
	s_lshl_b32 s2, s4, 1
	v_add_f32_e32 v32, v134, v32
	s_add_u32 s0, s0, s2
	v_div_scale_f32 v33, s[2:3], v32, v32, 1.0
	v_rcp_f32_e32 v34, v33
	s_addc_u32 s1, s1, 0
	v_mov_b32_e32 v123, v129
	v_fma_f32 v35, -v33, v34, 1.0
	v_fmac_f32_e32 v34, v35, v34
	v_div_scale_f32 v35, vcc, 1.0, v32, 1.0
	v_mul_f32_e32 v36, v35, v34
	v_fma_f32 v37, -v33, v36, v35
	v_fmac_f32_e32 v36, v37, v34
	v_fma_f32 v33, -v33, v36, v35
	v_div_fmas_f32 v33, v33, v34, v36
	v_div_fixup_f32 v34, v33, v32, 1.0
	v_lshlrev_b64 v[32:33], 11, v[120:121]
	v_lshl_add_u64 v[32:33], s[0:1], 0, v[32:33]
	v_mul_f32_e32 v16, v16, v34
	v_mul_f32_e32 v17, v17, v34
	v_mul_f32_e32 v18, v18, v34
	v_mul_f32_e32 v19, v19, v34
	v_mul_f32_e32 v0, v0, v34
	v_mul_f32_e32 v1, v1, v34
	v_mul_f32_e32 v2, v2, v34
	v_mul_f32_e32 v3, v3, v34
	v_lshl_add_u64 v[32:33], v[32:33], 0, v[122:123]
	v_cvt_pk_bf16_f32 v16, v16, v17
	v_cvt_pk_bf16_f32 v17, v18, v19
	v_cvt_pk_bf16_f32 v0, v0, v1
	v_cvt_pk_bf16_f32 v1, v2, v3
	v_and_b32_e32 v82, 31, v155
	v_bfe_u32 v83, v155, 3, 3
	v_lshrrev_b32_e32 v81, 6, v155
	v_mul_u32_u24_e32 v81, 0x1400, v81
	v_add_u32_e32 v81, 0x10000, v81
	v_mul_u32_u24_e32 v80, 0x90, v82
	v_mul_u32_u24_e32 v86, 0x90, v83
	v_add_u32_e32 v80, v80, v81
	v_add_u32_e32 v81, v86, v81
	v_sub_u32_e32 v87, v83, v82
	v_lshlrev_b32_e32 v87, 11, v87
	v_and_b32_e32 v83, 7, v155
	v_lshl_add_u32 v81, v83, 4, v81
	v_lshl_add_u32 v87, v83, 4, v87
	v_bfe_u32 v83, v155, 5, 1
	v_lshl_add_u32 v80, v83, 3, v80
	v_lshlrev_b32_e32 v83, 3, v83
	v_sub_u32_e32 v86, v87, v83
	v_add_u32_e32 v86, 0x400, v86
	v_ashrrev_i32_e32 v87, 31, v86
	v_lshl_add_u64 v[84:85], v[32:33], 0, v[86:87]
	v_mov_b32_e32 v86, 0x4000
	v_mov_b32_e32 v87, 0
	ds_write_b64 v80, v[16:17]
	v_mul_f32_e32 v16, v20, v34
	v_mul_f32_e32 v17, v21, v34
	v_mul_f32_e32 v18, v22, v34
	v_mul_f32_e32 v19, v23, v34
	ds_write_b64 v80, v[0:1] offset:64
	v_mul_f32_e32 v0, v4, v34
	v_mul_f32_e32 v1, v5, v34
	v_mul_f32_e32 v2, v6, v34
	v_mul_f32_e32 v3, v7, v34
	v_cvt_pk_bf16_f32 v16, v16, v17
	v_cvt_pk_bf16_f32 v17, v18, v19
	v_cvt_pk_bf16_f32 v0, v0, v1
	v_cvt_pk_bf16_f32 v1, v2, v3
	ds_write_b64 v80, v[16:17] offset:16
	v_mul_f32_e32 v16, v24, v34
	v_mul_f32_e32 v17, v25, v34
	v_mul_f32_e32 v18, v26, v34
	v_mul_f32_e32 v19, v27, v34
	ds_write_b64 v80, v[0:1] offset:80
	v_mul_f32_e32 v0, v8, v34
	v_mul_f32_e32 v1, v9, v34
	v_mul_f32_e32 v2, v10, v34
	v_mul_f32_e32 v3, v11, v34
	v_cvt_pk_bf16_f32 v16, v16, v17
	v_cvt_pk_bf16_f32 v17, v18, v19
	v_cvt_pk_bf16_f32 v0, v0, v1
	v_cvt_pk_bf16_f32 v1, v2, v3
	ds_write_b64 v80, v[16:17] offset:32
	v_mul_f32_e32 v16, v28, v34
	v_mul_f32_e32 v17, v29, v34
	v_mul_f32_e32 v18, v30, v34
	v_mul_f32_e32 v19, v31, v34
	ds_write_b64 v80, v[0:1] offset:96
	v_mul_f32_e32 v0, v12, v34
	v_mul_f32_e32 v1, v13, v34
	v_mul_f32_e32 v2, v14, v34
	v_mul_f32_e32 v3, v15, v34
	v_cvt_pk_bf16_f32 v16, v16, v17
	v_cvt_pk_bf16_f32 v17, v18, v19
	v_cvt_pk_bf16_f32 v0, v0, v1
	v_cvt_pk_bf16_f32 v1, v2, v3
	ds_write_b64 v80, v[16:17] offset:48
	ds_write_b64 v80, v[0:1] offset:112
	s_waitcnt lgkmcnt(0)
	ds_read_b128 v[64:67], v81 offset:0
	ds_read_b128 v[68:71], v81 offset:1152
	ds_read_b128 v[72:75], v81 offset:2304
	ds_read_b128 v[76:79], v81 offset:3456
	s_waitcnt lgkmcnt(3)
	global_store_dwordx4 v[84:85], v[64:67], off
	v_lshl_add_u64 v[84:85], v[84:85], 0, v[86:87]
	s_waitcnt lgkmcnt(2)
	global_store_dwordx4 v[84:85], v[68:71], off
	v_lshl_add_u64 v[84:85], v[84:85], 0, v[86:87]
	s_waitcnt lgkmcnt(1)
	global_store_dwordx4 v[84:85], v[72:75], off
	v_lshl_add_u64 v[84:85], v[84:85], 0, v[86:87]
	s_waitcnt lgkmcnt(0)
	global_store_dwordx4 v[84:85], v[76:79], off
	s_cbranch_execz .LBB0_1064
	s_branch .LBB0_1165

.LBB0_1164:
	v_readlane_b32 s0, v240, 7
	v_readlane_b32 s1, v240, 8
	v_mov_b32_e32 v0, v206
	s_lshl_b64 s[0:1], s[0:1], 11
	v_readlane_b32 s2, v241, 51
	v_permlane32_swap_b32_e32 v206, v0
	s_add_u32 s2, s2, s0
	v_readlane_b32 s0, v241, 52
	v_add_f32_e32 v0, v206, v0
	s_addc_u32 s3, s0, s1
	v_div_scale_f32 v1, s[0:1], v0, v0, 1.0
	v_rcp_f32_e32 v2, v1
	s_lshl_b32 s0, s29, 1
	s_add_u32 s0, s2, s0
	s_addc_u32 s1, s3, 0
	v_fma_f32 v3, -v1, v2, 1.0
	v_fmac_f32_e32 v2, v3, v2
	v_div_scale_f32 v3, vcc, 1.0, v0, 1.0
	v_mul_f32_e32 v4, v3, v2
	v_fma_f32 v5, -v1, v4, v3
	v_fmac_f32_e32 v4, v5, v2
	v_fma_f32 v1, -v1, v4, v3
	v_div_fmas_f32 v1, v1, v2, v4
	v_div_fixup_f32 v4, v1, v0, 1.0
	v_lshlrev_b64 v[0:1], 11, v[120:121]
	v_lshl_add_u64 v[0:1], s[0:1], 0, v[0:1]
	v_mov_b32_e32 v133, v129
	v_mul_f32_e32 v2, v48, v4
	v_mul_f32_e32 v3, v49, v4
	v_mul_f32_e32 v5, v50, v4
	v_mul_f32_e32 v6, v51, v4
	v_lshl_add_u64 v[0:1], v[132:133], 1, v[0:1]
	v_cvt_pk_bf16_f32 v2, v2, v3
	v_cvt_pk_bf16_f32 v3, v5, v6
	v_and_b32_e32 v82, 31, v155
	v_bfe_u32 v83, v155, 3, 3
	v_lshrrev_b32_e32 v81, 6, v155
	v_mul_u32_u24_e32 v81, 0x1400, v81
	v_add_u32_e32 v81, 0x10000, v81
	v_mul_u32_u24_e32 v80, 0x90, v82
	v_mul_u32_u24_e32 v86, 0x90, v83
	v_add_u32_e32 v80, v80, v81
	v_add_u32_e32 v81, v86, v81
	v_sub_u32_e32 v87, v83, v82
	v_lshlrev_b32_e32 v87, 11, v87
	v_and_b32_e32 v83, 7, v155
	v_lshl_add_u32 v81, v83, 4, v81
	v_lshl_add_u32 v87, v83, 4, v87
	v_bfe_u32 v83, v155, 5, 1
	v_lshl_add_u32 v80, v83, 3, v80
	v_lshlrev_b32_e32 v83, 3, v83
	v_sub_u32_e32 v86, v87, v83
	v_add_u32_e32 v86, 0x400, v86
	v_ashrrev_i32_e32 v87, 31, v86
	v_lshl_add_u64 v[84:85], v[0:1], 0, v[86:87]
	v_mov_b32_e32 v86, 0x4000
	v_mov_b32_e32 v87, 0
	ds_write_b64 v80, v[2:3]
	v_mul_f32_e32 v2, v52, v4
	v_mul_f32_e32 v3, v53, v4
	v_mul_f32_e32 v5, v54, v4
	v_mul_f32_e32 v6, v55, v4
	v_cvt_pk_bf16_f32 v2, v2, v3
	v_cvt_pk_bf16_f32 v3, v5, v6
	ds_write_b64 v80, v[2:3] offset:16
	v_mul_f32_e32 v2, v56, v4
	v_mul_f32_e32 v3, v57, v4
	v_mul_f32_e32 v5, v58, v4
	v_mul_f32_e32 v6, v59, v4
	v_cvt_pk_bf16_f32 v2, v2, v3
	v_cvt_pk_bf16_f32 v3, v5, v6
	ds_write_b64 v80, v[2:3] offset:32
	v_mul_f32_e32 v2, v60, v4
	v_mul_f32_e32 v3, v61, v4
	v_mul_f32_e32 v5, v62, v4
	v_mul_f32_e32 v6, v63, v4
	v_cvt_pk_bf16_f32 v2, v2, v3
	v_cvt_pk_bf16_f32 v3, v5, v6
	ds_write_b64 v80, v[2:3] offset:48
	v_mul_f32_e32 v2, v32, v4
	v_mul_f32_e32 v3, v33, v4
	v_mul_f32_e32 v5, v34, v4
	v_mul_f32_e32 v6, v35, v4
	v_cvt_pk_bf16_f32 v2, v2, v3
	v_cvt_pk_bf16_f32 v3, v5, v6
	ds_write_b64 v80, v[2:3] offset:64
	v_mul_f32_e32 v2, v36, v4
	v_mul_f32_e32 v3, v37, v4
	v_mul_f32_e32 v5, v38, v4
	v_mul_f32_e32 v6, v39, v4
	v_cvt_pk_bf16_f32 v2, v2, v3
	v_cvt_pk_bf16_f32 v3, v5, v6
	ds_write_b64 v80, v[2:3] offset:80
	v_mul_f32_e32 v2, v40, v4
	v_mul_f32_e32 v3, v41, v4
	v_mul_f32_e32 v5, v42, v4
	v_mul_f32_e32 v6, v43, v4
	v_cvt_pk_bf16_f32 v2, v2, v3
	v_cvt_pk_bf16_f32 v3, v5, v6
	v_readlane_b32 s38, v242, 2
	ds_write_b64 v80, v[2:3] offset:96
	v_mul_f32_e32 v2, v44, v4
	v_mul_f32_e32 v3, v45, v4
	v_mul_f32_e32 v5, v46, v4
	v_mul_f32_e32 v4, v47, v4
	v_readlane_b32 s39, v242, 3
	v_cvt_pk_bf16_f32 v2, v2, v3
	v_cvt_pk_bf16_f32 v3, v5, v4
	v_readlane_b32 s24, v241, 46
	v_readlane_b32 s25, v241, 47
	v_readlane_b32 s33, v241, 38
	s_mov_b32 s73, s35
	s_movk_i32 s31, 0x100
	s_movk_i32 s34, 0x300
	s_mov_b32 s35, 0x2aaaaaab
	s_movk_i32 s39, 0xff
	s_movk_i32 s80, 0x90
	v_readlane_b32 s26, v240, 9
	v_readlane_b32 s12, v240, 6
	ds_write_b64 v80, v[2:3] offset:112
	s_waitcnt lgkmcnt(0)
	ds_read_b128 v[64:67], v81 offset:0
	ds_read_b128 v[68:71], v81 offset:1152
	ds_read_b128 v[72:75], v81 offset:2304
	ds_read_b128 v[76:79], v81 offset:3456
	s_waitcnt lgkmcnt(3)
	global_store_dwordx4 v[84:85], v[64:67], off
	v_lshl_add_u64 v[84:85], v[84:85], 0, v[86:87]
	s_waitcnt lgkmcnt(2)
	global_store_dwordx4 v[84:85], v[68:71], off
	v_lshl_add_u64 v[84:85], v[84:85], 0, v[86:87]
	s_waitcnt lgkmcnt(1)
	global_store_dwordx4 v[84:85], v[72:75], off
	v_lshl_add_u64 v[84:85], v[84:85], 0, v[86:87]
	s_waitcnt lgkmcnt(0)
	global_store_dwordx4 v[84:85], v[76:79], off
